# gate+qkv 256-tile epilogues: bf16 tile transposed through LDS so every wave store covers full 512-byte row segments (dwordx4); pieces K-loops on a 4-stage LDS-DMA ring
# speedup vs baseline: 1.1727x; 1.0306x over previous
.LBB0_15:
	s_ashr_i32 s0, s12, 3
	s_addk_i32 s0, 0x400
	s_lshr_b32 s1, s0, 29
	s_add_i32 s1, s0, s1
	s_ashr_i32 s8, s1, 3
	s_and_b32 s1, s1, -8
	s_sub_i32 s0, s0, s1
	s_lshr_b32 s1, s0, 31
	s_or_b32 s1, s1, 0x84
	s_mul_i32 s0, s1, s0
	s_add_i32 s8, s0, s8
	s_mul_hi_i32 s0, s8, 0x2aaaaaab
	s_lshr_b32 s1, s0, 31
	s_ashr_i32 s0, s0, 5
	s_add_i32 s9, s0, s1
	s_lshl_b32 s13, s9, 2
	s_sub_i32 s0, 22, s13
	s_min_u32 s16, s0, 4
	s_mul_i32 s17, s9, 0xc0
	s_sub_i32 s52, s8, s17
	v_cvt_f32_ubyte0_e32 v2, s16
	v_cvt_f32_i32_e32 v0, s52
	v_rcp_iflag_f32_e32 v3, v2
	s_ashr_i32 s0, s52, 30
	s_and_b32 s14, s11, 0xc0
	s_and_b32 s15, s10, 0x80
	v_mul_f32_e32 v3, v0, v3
	v_trunc_f32_e32 v3, v3
	v_fma_f32 v0, -v3, v2, v0
	v_cvt_i32_f32_e32 v3, v3
	s_or_b32 s53, s0, 1
	v_cmp_ge_f32_e64 s[0:1], |v0|, v2
	s_and_b64 s[0:1], s[0:1], exec
	s_cselect_b32 s0, s53, 0
	v_readfirstlane_b32 s1, v3
	s_add_i32 s0, s1, s0
	s_mul_i32 s16, s0, s16
	s_sext_i32_i16 s1, s0
	s_sub_i32 s0, s52, s16
	s_sext_i32_i16 s0, s0
	s_add_i32 s13, s13, s0
	s_lshl_b32 s0, s13, 8
	s_lshl_b32 s13, s12, 5
	s_lshl_b32 s52, s1, 8
	s_lshl_b32 s1, s12, 7
	s_and_b32 s13, s13, 0xc0
	s_and_b32 s1, s1, 0x80
	v_mov_b32_e32 v8, v206
	s_barrier
	s_or_b32 s0, s0, s13
	s_or_b32 s1, s52, s1
	s_or_b32 s13, s0, 63
	v_ashrrev_i32_e32 v9, 3, v8
	v_add_u32_e32 v2, s1, v9
	v_add_u32_e32 v4, s0, v9
	v_ashrrev_i32_e32 v3, 31, v2
	v_min_i32_e32 v4, s13, v4
	v_lshlrev_b64 v[2:3], 12, v[2:3]
	v_lshlrev_b32_e32 v0, 4, v8
	v_ashrrev_i32_e32 v5, 31, v4
	v_lshl_add_u64 v[2:3], s[88:89], 0, v[2:3]
	v_and_b32_e32 v0, 0x70, v0
	v_lshlrev_b64 v[4:5], 12, v[4:5]
	v_lshl_add_u64 v[2:3], v[2:3], 0, v[0:1]
	v_lshl_add_u64 v[4:5], s[6:7], 0, v[4:5]
	s_mov_b32 s13, 0x40000
	v_lshl_add_u64 v[4:5], v[4:5], 0, v[0:1]
	v_add_co_u32_e32 v6, vcc, s13, v2
	v_lshrrev_b32_e32 v0, 4, v8
	s_nop 0
	v_addc_co_u32_e32 v7, vcc, 0, v3, vcc
	s_sub_i32 s8, s8, s16
	v_xor_b32_e32 v2, v0, v8
	s_sub_i32 s8, s8, s17
	v_and_b32_e32 v53, 15, v8
	v_bfe_u32 v3, v8, 1, 3
	v_lshlrev_b32_e32 v2, 4, v2
	s_sext_i32_i16 s8, s8
	v_bfe_u32 v51, v8, 6, 2
	v_ashrrev_i32_e32 v50, 8, v8
	v_and_b32_e32 v2, 0x70, v2
	v_lshlrev_b32_e32 v4, 7, v53
	v_bitop3_b32 v0, v0, v3, 3 bitop3:0x6c
	s_lshl_b32 s53, s9, 10
	s_lshl_b32 s16, s8, 8
	v_bfe_u32 v52, v8, 4, 2
	v_lshl_or_b32 v54, v9, 7, v2
	v_lshl_or_b32 v2, v51, 11, v4
	v_lshlrev_b32_e32 v0, 4, v0
	v_lshlrev_b32_e32 v5, 13, v50
	s_add_i32 s8, s53, s16
	v_or_b32_e32 v6, v0, v5
	v_or_b32_e32 v55, v2, v0
	v_bitop3_b32 v0, v52, v3, 4 bitop3:0x36
	s_or_b32 s8, s8, s14
	s_or_b32 s14, s14, s16
	v_lshlrev_b32_e32 v0, 4, v0
	s_add_i32 s14, s14, s53
	v_or_b32_e32 v56, v2, v0
	v_add_u32_e32 v2, s14, v9
	s_ashr_i32 s9, s8, 31
	s_or_b32 s8, s8, 63
	v_ashrrev_i32_e32 v3, 31, v2
	v_mov_b32_e32 v7, s9
	v_cmp_lt_i64_e32 vcc, s[8:9], v[2:3]
	v_or_b32_e32 v5, v0, v5
	v_and_b32_e32 v0, 7, v8
	v_cndmask_b32_e32 v3, v3, v7, vcc
	v_mov_b32_e32 v7, s8
	v_cndmask_b32_e32 v2, v2, v7, vcc
	v_lshlrev_b64 v[2:3], 12, v[2:3]
	s_or_b32 s8, s15, s52
	v_lshl_add_u64 v[42:43], s[6:7], 0, v[2:3]
	v_add_u32_e32 v2, s8, v9
	v_ashrrev_i32_e32 v3, 31, v2
	v_lshlrev_b64 v[2:3], 12, v[2:3]
	v_mov_b32_e32 v26, 0
	s_mov_b32 s13, 0
	v_lshlrev_b32_e32 v0, 4, v0
	v_lshl_add_u64 v[44:45], s[88:89], 0, v[2:3]
	v_add_u32_e32 v57, v6, v4
	v_add_u32_e32 v58, v5, v4
	v_mov_b32_e32 v27, v26
	v_mov_b32_e32 v28, v26
	v_mov_b32_e32 v29, v26
	s_waitcnt vmcnt(0)
	v_mov_b32_e32 v22, v26
	v_mov_b32_e32 v23, v26
	v_mov_b32_e32 v24, v26
	v_mov_b32_e32 v25, v26
	v_mov_b32_e32 v6, v26
	v_mov_b32_e32 v7, v26
	v_mov_b32_e32 v8, v26
	v_mov_b32_e32 v9, v26
	v_mov_b32_e32 v2, v26
	v_mov_b32_e32 v3, v26
	v_mov_b32_e32 v4, v26
	v_mov_b32_e32 v5, v26
	v_lshrrev_b32_e32 v106, 4, v206
	v_xor_b32_e32 v106, v106, v206
	v_and_b32_e32 v106, 7, v106
	v_lshlrev_b32_e32 v106, 4, v106
	v_mov_b32_e32 v107, 0
	v_lshrrev_b32_e32 v108, 6, v206
	v_lshl_add_u64 v[100:101], v[44:45], 0, v[106:107]
	v_lshl_add_u64 v[104:105], v[42:43], 0, v[106:107]
	s_mov_b64 s[14:15], 0x40000
	v_readfirstlane_b32 s13, v108
	v_lshl_add_u64 v[102:103], v[100:101], 0, s[14:15]
	s_mov_b64 s[14:15], 0x80
	s_lshl_b32 s13, s13, 10
	v_add_u32_e32 v110, 0xc000, v55
	v_add_u32_e32 v111, 0xc000, v56
	v_add_u32_e32 v112, 0xc000, v57
	v_add_u32_e32 v113, 0xc000, v58
	s_mov_b32 m0, s13
	s_nop 0
	global_load_lds_dwordx4 v[100:101], off
	s_add_u32 m0, s13, 0x2000
	v_lshl_add_u64 v[100:101], v[100:101], 0, s[14:15]
	global_load_lds_dwordx4 v[102:103], off
	s_add_u32 m0, s13, 0x4000
	v_lshl_add_u64 v[102:103], v[102:103], 0, s[14:15]
	global_load_lds_dwordx4 v[104:105], off
	v_lshl_add_u64 v[104:105], v[104:105], 0, s[14:15]
	s_add_u32 m0, s13, 0x6000
	s_nop 0
	global_load_lds_dwordx4 v[100:101], off
	s_add_u32 m0, s13, 0x8000
	v_lshl_add_u64 v[100:101], v[100:101], 0, s[14:15]
	global_load_lds_dwordx4 v[102:103], off
	s_add_u32 m0, s13, 0xa000
	v_lshl_add_u64 v[102:103], v[102:103], 0, s[14:15]
	global_load_lds_dwordx4 v[104:105], off
	v_lshl_add_u64 v[104:105], v[104:105], 0, s[14:15]
	s_add_u32 m0, s13, 0xc000
	s_nop 0
	global_load_lds_dwordx4 v[100:101], off
	s_add_u32 m0, s13, 0xe000
	v_lshl_add_u64 v[100:101], v[100:101], 0, s[14:15]
	global_load_lds_dwordx4 v[102:103], off
	s_add_u32 m0, s13, 0x10000
	v_lshl_add_u64 v[102:103], v[102:103], 0, s[14:15]
	global_load_lds_dwordx4 v[104:105], off
	v_lshl_add_u64 v[104:105], v[104:105], 0, s[14:15]
	s_mov_b32 s8, 0
.Lpcs_u_loop:
	s_waitcnt vmcnt(6)
	s_barrier
	s_add_u32 m0, s13, 0x12000
	s_nop 0
	global_load_lds_dwordx4 v[100:101], off
	s_add_u32 m0, s13, 0x14000
	v_lshl_add_u64 v[100:101], v[100:101], 0, s[14:15]
	global_load_lds_dwordx4 v[102:103], off
	s_add_u32 m0, s13, 0x16000
	v_lshl_add_u64 v[102:103], v[102:103], 0, s[14:15]
	global_load_lds_dwordx4 v[104:105], off
	v_lshl_add_u64 v[104:105], v[104:105], 0, s[14:15]
	ds_read_b128 v[60:63], v55 offset:16384
	ds_read_b128 v[64:67], v57
	ds_read_b128 v[68:71], v57 offset:2048
	ds_read_b128 v[72:75], v57 offset:4096
	ds_read_b128 v[76:79], v57 offset:6144
	ds_read_b128 v[80:83], v56 offset:16384
	ds_read_b128 v[84:87], v58
	ds_read_b128 v[88:91], v58 offset:2048
	ds_read_b128 v[92:95], v58 offset:4096
	ds_read_b128 v[96:99], v58 offset:6144
	s_waitcnt lgkmcnt(8)
	v_mfma_f32_16x16x32_bf16 v[26:29], v[60:63], v[64:67], v[26:29]
	s_waitcnt lgkmcnt(7)
	v_mfma_f32_16x16x32_bf16 v[22:25], v[60:63], v[68:71], v[22:25]
	s_waitcnt lgkmcnt(6)
	v_mfma_f32_16x16x32_bf16 v[6:9], v[60:63], v[72:75], v[6:9]
	s_waitcnt lgkmcnt(5)
	v_mfma_f32_16x16x32_bf16 v[2:5], v[60:63], v[76:79], v[2:5]
	s_waitcnt lgkmcnt(3)
	v_mfma_f32_16x16x32_bf16 v[26:29], v[80:83], v[84:87], v[26:29]
	s_waitcnt lgkmcnt(2)
	v_mfma_f32_16x16x32_bf16 v[22:25], v[80:83], v[88:91], v[22:25]
	s_waitcnt lgkmcnt(1)
	v_mfma_f32_16x16x32_bf16 v[6:9], v[80:83], v[92:95], v[6:9]
	s_waitcnt lgkmcnt(0)
	v_mfma_f32_16x16x32_bf16 v[2:5], v[80:83], v[96:99], v[2:5]
	s_waitcnt vmcnt(6)
	s_barrier
	s_mov_b32 m0, s13
	s_nop 0
	global_load_lds_dwordx4 v[100:101], off
	s_add_u32 m0, s13, 0x2000
	v_lshl_add_u64 v[100:101], v[100:101], 0, s[14:15]
	global_load_lds_dwordx4 v[102:103], off
	s_add_u32 m0, s13, 0x4000
	v_lshl_add_u64 v[102:103], v[102:103], 0, s[14:15]
	global_load_lds_dwordx4 v[104:105], off
	v_lshl_add_u64 v[104:105], v[104:105], 0, s[14:15]
	ds_read_b128 v[60:63], v55 offset:40960
	ds_read_b128 v[64:67], v57 offset:24576
	ds_read_b128 v[68:71], v57 offset:26624
	ds_read_b128 v[72:75], v57 offset:28672
	ds_read_b128 v[76:79], v57 offset:30720
	ds_read_b128 v[80:83], v56 offset:40960
	ds_read_b128 v[84:87], v58 offset:24576
	ds_read_b128 v[88:91], v58 offset:26624
	ds_read_b128 v[92:95], v58 offset:28672
	ds_read_b128 v[96:99], v58 offset:30720
	s_waitcnt lgkmcnt(8)
	v_mfma_f32_16x16x32_bf16 v[26:29], v[60:63], v[64:67], v[26:29]
	s_waitcnt lgkmcnt(7)
	v_mfma_f32_16x16x32_bf16 v[22:25], v[60:63], v[68:71], v[22:25]
	s_waitcnt lgkmcnt(6)
	v_mfma_f32_16x16x32_bf16 v[6:9], v[60:63], v[72:75], v[6:9]
	s_waitcnt lgkmcnt(5)
	v_mfma_f32_16x16x32_bf16 v[2:5], v[60:63], v[76:79], v[2:5]
	s_waitcnt lgkmcnt(3)
	v_mfma_f32_16x16x32_bf16 v[26:29], v[80:83], v[84:87], v[26:29]
	s_waitcnt lgkmcnt(2)
	v_mfma_f32_16x16x32_bf16 v[22:25], v[80:83], v[88:91], v[22:25]
	s_waitcnt lgkmcnt(1)
	v_mfma_f32_16x16x32_bf16 v[6:9], v[80:83], v[92:95], v[6:9]
	s_waitcnt lgkmcnt(0)
	v_mfma_f32_16x16x32_bf16 v[2:5], v[80:83], v[96:99], v[2:5]
	s_waitcnt vmcnt(6)
	s_barrier
	s_add_u32 m0, s13, 0x6000
	s_nop 0
	global_load_lds_dwordx4 v[100:101], off
	s_add_u32 m0, s13, 0x8000
	v_lshl_add_u64 v[100:101], v[100:101], 0, s[14:15]
	global_load_lds_dwordx4 v[102:103], off
	s_add_u32 m0, s13, 0xa000
	v_lshl_add_u64 v[102:103], v[102:103], 0, s[14:15]
	global_load_lds_dwordx4 v[104:105], off
	v_lshl_add_u64 v[104:105], v[104:105], 0, s[14:15]
	ds_read_b128 v[60:63], v110 offset:16384
	ds_read_b128 v[64:67], v112
	ds_read_b128 v[68:71], v112 offset:2048
	ds_read_b128 v[72:75], v112 offset:4096
	ds_read_b128 v[76:79], v112 offset:6144
	ds_read_b128 v[80:83], v111 offset:16384
	ds_read_b128 v[84:87], v113
	ds_read_b128 v[88:91], v113 offset:2048
	ds_read_b128 v[92:95], v113 offset:4096
	ds_read_b128 v[96:99], v113 offset:6144
	s_waitcnt lgkmcnt(8)
	v_mfma_f32_16x16x32_bf16 v[26:29], v[60:63], v[64:67], v[26:29]
	s_waitcnt lgkmcnt(7)
	v_mfma_f32_16x16x32_bf16 v[22:25], v[60:63], v[68:71], v[22:25]
	s_waitcnt lgkmcnt(6)
	v_mfma_f32_16x16x32_bf16 v[6:9], v[60:63], v[72:75], v[6:9]
	s_waitcnt lgkmcnt(5)
	v_mfma_f32_16x16x32_bf16 v[2:5], v[60:63], v[76:79], v[2:5]
	s_waitcnt lgkmcnt(3)
	v_mfma_f32_16x16x32_bf16 v[26:29], v[80:83], v[84:87], v[26:29]
	s_waitcnt lgkmcnt(2)
	v_mfma_f32_16x16x32_bf16 v[22:25], v[80:83], v[88:91], v[22:25]
	s_waitcnt lgkmcnt(1)
	v_mfma_f32_16x16x32_bf16 v[6:9], v[80:83], v[92:95], v[6:9]
	s_waitcnt lgkmcnt(0)
	v_mfma_f32_16x16x32_bf16 v[2:5], v[80:83], v[96:99], v[2:5]
	s_waitcnt vmcnt(6)
	s_barrier
	s_add_u32 m0, s13, 0xc000
	s_nop 0
	global_load_lds_dwordx4 v[100:101], off
	s_add_u32 m0, s13, 0xe000
	v_lshl_add_u64 v[100:101], v[100:101], 0, s[14:15]
	global_load_lds_dwordx4 v[102:103], off
	s_add_u32 m0, s13, 0x10000
	v_lshl_add_u64 v[102:103], v[102:103], 0, s[14:15]
	global_load_lds_dwordx4 v[104:105], off
	v_lshl_add_u64 v[104:105], v[104:105], 0, s[14:15]
	ds_read_b128 v[60:63], v110 offset:40960
	ds_read_b128 v[64:67], v112 offset:24576
	ds_read_b128 v[68:71], v112 offset:26624
	ds_read_b128 v[72:75], v112 offset:28672
	ds_read_b128 v[76:79], v112 offset:30720
	ds_read_b128 v[80:83], v111 offset:40960
	ds_read_b128 v[84:87], v113 offset:24576
	ds_read_b128 v[88:91], v113 offset:26624
	ds_read_b128 v[92:95], v113 offset:28672
	ds_read_b128 v[96:99], v113 offset:30720
	s_waitcnt lgkmcnt(8)
	v_mfma_f32_16x16x32_bf16 v[26:29], v[60:63], v[64:67], v[26:29]
	s_waitcnt lgkmcnt(7)
	v_mfma_f32_16x16x32_bf16 v[22:25], v[60:63], v[68:71], v[22:25]
	s_waitcnt lgkmcnt(6)
	v_mfma_f32_16x16x32_bf16 v[6:9], v[60:63], v[72:75], v[6:9]
	s_waitcnt lgkmcnt(5)
	v_mfma_f32_16x16x32_bf16 v[2:5], v[60:63], v[76:79], v[2:5]
	s_waitcnt lgkmcnt(3)
	v_mfma_f32_16x16x32_bf16 v[26:29], v[80:83], v[84:87], v[26:29]
	s_waitcnt lgkmcnt(2)
	v_mfma_f32_16x16x32_bf16 v[22:25], v[80:83], v[88:91], v[22:25]
	s_waitcnt lgkmcnt(1)
	v_mfma_f32_16x16x32_bf16 v[6:9], v[80:83], v[92:95], v[6:9]
	s_waitcnt lgkmcnt(0)
	v_mfma_f32_16x16x32_bf16 v[2:5], v[80:83], v[96:99], v[2:5]
	s_add_i32 s8, s8, 1
	s_cmp_lt_u32 s8, 7
	s_cbranch_scc1 .Lpcs_u_loop
	s_waitcnt vmcnt(6)
	s_barrier
	s_add_u32 m0, s13, 0x12000
	s_nop 0
	global_load_lds_dwordx4 v[100:101], off
	s_add_u32 m0, s13, 0x14000
	v_lshl_add_u64 v[100:101], v[100:101], 0, s[14:15]
	global_load_lds_dwordx4 v[102:103], off
	s_add_u32 m0, s13, 0x16000
	v_lshl_add_u64 v[102:103], v[102:103], 0, s[14:15]
	global_load_lds_dwordx4 v[104:105], off
	v_lshl_add_u64 v[104:105], v[104:105], 0, s[14:15]
	ds_read_b128 v[60:63], v55 offset:16384
	ds_read_b128 v[64:67], v57
	ds_read_b128 v[68:71], v57 offset:2048
	ds_read_b128 v[72:75], v57 offset:4096
	ds_read_b128 v[76:79], v57 offset:6144
	ds_read_b128 v[80:83], v56 offset:16384
	ds_read_b128 v[84:87], v58
	ds_read_b128 v[88:91], v58 offset:2048
	ds_read_b128 v[92:95], v58 offset:4096
	ds_read_b128 v[96:99], v58 offset:6144
	s_waitcnt lgkmcnt(8)
	v_mfma_f32_16x16x32_bf16 v[26:29], v[60:63], v[64:67], v[26:29]
	s_waitcnt lgkmcnt(7)
	v_mfma_f32_16x16x32_bf16 v[22:25], v[60:63], v[68:71], v[22:25]
	s_waitcnt lgkmcnt(6)
	v_mfma_f32_16x16x32_bf16 v[6:9], v[60:63], v[72:75], v[6:9]
	s_waitcnt lgkmcnt(5)
	v_mfma_f32_16x16x32_bf16 v[2:5], v[60:63], v[76:79], v[2:5]
	s_waitcnt lgkmcnt(3)
	v_mfma_f32_16x16x32_bf16 v[26:29], v[80:83], v[84:87], v[26:29]
	s_waitcnt lgkmcnt(2)
	v_mfma_f32_16x16x32_bf16 v[22:25], v[80:83], v[88:91], v[22:25]
	s_waitcnt lgkmcnt(1)
	v_mfma_f32_16x16x32_bf16 v[6:9], v[80:83], v[92:95], v[6:9]
	s_waitcnt lgkmcnt(0)
	v_mfma_f32_16x16x32_bf16 v[2:5], v[80:83], v[96:99], v[2:5]
	s_waitcnt vmcnt(6)
	s_barrier
	ds_read_b128 v[60:63], v55 offset:40960
	ds_read_b128 v[64:67], v57 offset:24576
	ds_read_b128 v[68:71], v57 offset:26624
	ds_read_b128 v[72:75], v57 offset:28672
	ds_read_b128 v[76:79], v57 offset:30720
	ds_read_b128 v[80:83], v56 offset:40960
	ds_read_b128 v[84:87], v58 offset:24576
	ds_read_b128 v[88:91], v58 offset:26624
	ds_read_b128 v[92:95], v58 offset:28672
	ds_read_b128 v[96:99], v58 offset:30720
	s_waitcnt lgkmcnt(8)
	v_mfma_f32_16x16x32_bf16 v[26:29], v[60:63], v[64:67], v[26:29]
	s_waitcnt lgkmcnt(7)
	v_mfma_f32_16x16x32_bf16 v[22:25], v[60:63], v[68:71], v[22:25]
	s_waitcnt lgkmcnt(6)
	v_mfma_f32_16x16x32_bf16 v[6:9], v[60:63], v[72:75], v[6:9]
	s_waitcnt lgkmcnt(5)
	v_mfma_f32_16x16x32_bf16 v[2:5], v[60:63], v[76:79], v[2:5]
	s_waitcnt lgkmcnt(3)
	v_mfma_f32_16x16x32_bf16 v[26:29], v[80:83], v[84:87], v[26:29]
	s_waitcnt lgkmcnt(2)
	v_mfma_f32_16x16x32_bf16 v[22:25], v[80:83], v[88:91], v[22:25]
	s_waitcnt lgkmcnt(1)
	v_mfma_f32_16x16x32_bf16 v[6:9], v[80:83], v[92:95], v[6:9]
	s_waitcnt lgkmcnt(0)
	v_mfma_f32_16x16x32_bf16 v[2:5], v[80:83], v[96:99], v[2:5]
	s_waitcnt vmcnt(3)
	s_barrier
	ds_read_b128 v[60:63], v110 offset:16384
	ds_read_b128 v[64:67], v112
	ds_read_b128 v[68:71], v112 offset:2048
	ds_read_b128 v[72:75], v112 offset:4096
	ds_read_b128 v[76:79], v112 offset:6144
	ds_read_b128 v[80:83], v111 offset:16384
	ds_read_b128 v[84:87], v113
	ds_read_b128 v[88:91], v113 offset:2048
	ds_read_b128 v[92:95], v113 offset:4096
	ds_read_b128 v[96:99], v113 offset:6144
	s_waitcnt lgkmcnt(8)
	v_mfma_f32_16x16x32_bf16 v[26:29], v[60:63], v[64:67], v[26:29]
	s_waitcnt lgkmcnt(7)
	v_mfma_f32_16x16x32_bf16 v[22:25], v[60:63], v[68:71], v[22:25]
	s_waitcnt lgkmcnt(6)
	v_mfma_f32_16x16x32_bf16 v[6:9], v[60:63], v[72:75], v[6:9]
	s_waitcnt lgkmcnt(5)
	v_mfma_f32_16x16x32_bf16 v[2:5], v[60:63], v[76:79], v[2:5]
	s_waitcnt lgkmcnt(3)
	v_mfma_f32_16x16x32_bf16 v[26:29], v[80:83], v[84:87], v[26:29]
	s_waitcnt lgkmcnt(2)
	v_mfma_f32_16x16x32_bf16 v[22:25], v[80:83], v[88:91], v[22:25]
	s_waitcnt lgkmcnt(1)
	v_mfma_f32_16x16x32_bf16 v[6:9], v[80:83], v[92:95], v[6:9]
	s_waitcnt lgkmcnt(0)
	v_mfma_f32_16x16x32_bf16 v[2:5], v[80:83], v[96:99], v[2:5]
	s_waitcnt vmcnt(0)
	s_barrier
	ds_read_b128 v[60:63], v110 offset:40960
	ds_read_b128 v[64:67], v112 offset:24576
	ds_read_b128 v[68:71], v112 offset:26624
	ds_read_b128 v[72:75], v112 offset:28672
	ds_read_b128 v[76:79], v112 offset:30720
	ds_read_b128 v[80:83], v111 offset:40960
	ds_read_b128 v[84:87], v113 offset:24576
	ds_read_b128 v[88:91], v113 offset:26624
	ds_read_b128 v[92:95], v113 offset:28672
	ds_read_b128 v[96:99], v113 offset:30720
	s_waitcnt lgkmcnt(8)
	v_mfma_f32_16x16x32_bf16 v[26:29], v[60:63], v[64:67], v[26:29]
	s_waitcnt lgkmcnt(7)
	v_mfma_f32_16x16x32_bf16 v[22:25], v[60:63], v[68:71], v[22:25]
	s_waitcnt lgkmcnt(6)
	v_mfma_f32_16x16x32_bf16 v[6:9], v[60:63], v[72:75], v[6:9]
	s_waitcnt lgkmcnt(5)
	v_mfma_f32_16x16x32_bf16 v[2:5], v[60:63], v[76:79], v[2:5]
	s_waitcnt lgkmcnt(3)
	v_mfma_f32_16x16x32_bf16 v[26:29], v[80:83], v[84:87], v[26:29]
	s_waitcnt lgkmcnt(2)
	v_mfma_f32_16x16x32_bf16 v[22:25], v[80:83], v[88:91], v[22:25]
	s_waitcnt lgkmcnt(1)
	v_mfma_f32_16x16x32_bf16 v[6:9], v[80:83], v[92:95], v[6:9]
	s_waitcnt lgkmcnt(0)
	v_mfma_f32_16x16x32_bf16 v[2:5], v[80:83], v[96:99], v[2:5]
	s_branch .LBB0_21

.LBB0_75:
	s_ashr_i32 s6, s8, 3
	s_addk_i32 s6, 0x400
	s_lshr_b32 s7, s6, 29
	s_add_i32 s7, s6, s7
	s_ashr_i32 s9, s7, 3
	s_and_b32 s7, s7, -8
	s_sub_i32 s6, s6, s7
	s_lshr_b32 s7, s6, 31
	s_or_b32 s7, s7, 0x84
	s_mul_i32 s6, s7, s6
	s_add_i32 s14, s6, s9
	s_mul_hi_i32 s6, s14, 0x2aaaaaab
	s_lshr_b32 s7, s6, 31
	s_ashr_i32 s6, s6, 5
	s_add_i32 s15, s6, s7
	s_lshl_b32 s9, s15, 2
	s_sub_i32 s6, 22, s9
	s_min_u32 s10, s6, 4
	s_mul_i32 s16, s15, 0xc0
	s_sub_i32 s11, s14, s16
	v_cvt_f32_ubyte0_e32 v2, s10
	v_cvt_f32_i32_e32 v0, s11
	v_rcp_iflag_f32_e32 v3, v2
	s_ashr_i32 s6, s11, 30
	s_and_b32 s12, s1, 0xc0
	s_and_b32 s13, s0, 0x80
	v_mul_f32_e32 v3, v0, v3
	v_trunc_f32_e32 v3, v3
	v_fma_f32 v0, -v3, v2, v0
	v_cvt_i32_f32_e32 v3, v3
	s_or_b32 s17, s6, 1
	v_cmp_ge_f32_e64 s[6:7], |v0|, v2
	s_and_b64 s[6:7], s[6:7], exec
	s_cselect_b32 s6, s17, 0
	v_readfirstlane_b32 s7, v3
	s_add_i32 s6, s7, s6
	s_sext_i32_i16 s7, s6
	s_mul_i32 s6, s6, s10
	s_sub_i32 s10, s11, s6
	s_sext_i32_i16 s10, s10
	s_add_i32 s9, s9, s10
	s_lshl_b32 s10, s8, 5
	s_lshl_b32 s17, s7, 8
	s_lshl_b32 s7, s8, 7
	s_lshl_b32 s9, s9, 8
	s_and_b32 s10, s10, 0xc0
	s_and_b32 s7, s7, 0x80
	v_mov_b32_e32 v26, v206
	s_barrier
	s_or_b32 s10, s9, s10
	s_or_b32 s9, s17, s7
	s_or_b32 s7, s10, 63
	v_ashrrev_i32_e32 v28, 3, v26
	v_add_u32_e32 v2, s9, v28
	v_ashrrev_i32_e32 v3, 31, v2
	v_lshlrev_b64 v[2:3], 12, v[2:3]
	v_lshlrev_b32_e32 v0, 4, v26
	v_lshl_add_u64 v[2:3], s[88:89], 0, v[2:3]
	v_and_b32_e32 v0, 0x70, v0
	s_waitcnt vmcnt(0)
	v_lshl_add_u64 v[18:19], v[2:3], 0, v[0:1]
	v_add_u32_e32 v2, s10, v28
	v_min_i32_e32 v2, s7, v2
	v_ashrrev_i32_e32 v3, 31, v2
	v_lshlrev_b64 v[2:3], 12, v[2:3]
	s_mov_b32 s7, 0x40000
	v_lshl_add_u64 v[2:3], s[4:5], 0, v[2:3]
	v_add_co_u32_e32 v4, vcc, s7, v18
	v_lshl_add_u64 v[2:3], v[2:3], 0, v[0:1]
	s_nop 0
	v_addc_co_u32_e32 v5, vcc, 0, v19, vcc
	s_nop 0
	s_nop 0
	v_lshrrev_b32_e32 v0, 4, v26
	s_sub_i32 s6, s14, s6
	v_xor_b32_e32 v27, v0, v26
	s_sub_i32 s6, s6, s16
	v_and_b32_e32 v51, 15, v26
	v_bfe_u32 v29, v26, 1, 3
	v_lshlrev_b32_e32 v27, 4, v27
	s_sext_i32_i16 s6, s6
	v_bfe_u32 v52, v26, 6, 2
	v_ashrrev_i32_e32 v50, 8, v26
	v_and_b32_e32 v27, 0x70, v27
	v_lshlrev_b32_e32 v30, 7, v51
	v_bitop3_b32 v0, v0, v29, 3 bitop3:0x6c
	s_lshl_b32 s15, s15, 10
	s_lshl_b32 s14, s6, 8
	v_bfe_u32 v53, v26, 4, 2
	v_lshl_or_b32 v54, v28, 7, v27
	v_lshl_or_b32 v27, v52, 11, v30
	v_lshlrev_b32_e32 v0, 4, v0
	v_lshlrev_b32_e32 v31, 13, v50
	s_add_i32 s6, s15, s14
	v_or_b32_e32 v32, v0, v31
	v_or_b32_e32 v55, v27, v0
	v_bitop3_b32 v0, v53, v29, 4 bitop3:0x36
	s_or_b32 s6, s6, s12
	s_or_b32 s12, s12, s14
	v_lshlrev_b32_e32 v0, 4, v0
	s_add_i32 s12, s12, s15
	v_or_b32_e32 v29, v0, v31
	v_or_b32_e32 v56, v27, v0
	v_and_b32_e32 v0, 7, v26
	v_add_u32_e32 v26, s12, v28
	s_ashr_i32 s7, s6, 31
	s_or_b32 s6, s6, 63
	v_ashrrev_i32_e32 v27, 31, v26
	v_mov_b32_e32 v31, s7
	v_cmp_lt_i64_e32 vcc, s[6:7], v[26:27]
	s_mov_b32 s11, 0
	v_lshlrev_b32_e32 v0, 4, v0
	v_cndmask_b32_e32 v27, v27, v31, vcc
	v_mov_b32_e32 v31, s6
	v_cndmask_b32_e32 v26, v26, v31, vcc
	v_lshlrev_b64 v[26:27], 12, v[26:27]
	s_or_b32 s6, s13, s17
	v_lshl_add_u64 v[42:43], s[4:5], 0, v[26:27]
	v_add_u32_e32 v26, s6, v28
	v_ashrrev_i32_e32 v27, 31, v26
	v_lshlrev_b64 v[26:27], 12, v[26:27]
	v_lshl_add_u64 v[44:45], s[88:89], 0, v[26:27]
	v_mov_b32_e32 v26, 0
	v_add_u32_e32 v57, v32, v30
	v_add_u32_e32 v58, v29, v30
	v_mov_b32_e32 v27, v26
	v_mov_b32_e32 v28, v26
	v_mov_b32_e32 v29, v26
	v_mov_b32_e32 v30, v26
	v_mov_b32_e32 v31, v26
	v_mov_b32_e32 v32, v26
	v_mov_b32_e32 v33, v26
	v_mov_b32_e32 v38, v26
	v_mov_b32_e32 v39, v26
	v_mov_b32_e32 v40, v26
	v_mov_b32_e32 v41, v26
	v_mov_b32_e32 v34, v26
	v_mov_b32_e32 v35, v26
	v_mov_b32_e32 v36, v26
	v_mov_b32_e32 v37, v26
	v_lshrrev_b32_e32 v106, 4, v206
	v_xor_b32_e32 v106, v106, v206
	v_and_b32_e32 v106, 7, v106
	v_lshlrev_b32_e32 v106, 4, v106
	v_mov_b32_e32 v107, 0
	v_lshrrev_b32_e32 v108, 6, v206
	v_lshl_add_u64 v[100:101], v[44:45], 0, v[106:107]
	v_lshl_add_u64 v[104:105], v[42:43], 0, v[106:107]
	s_mov_b64 s[12:13], 0x40000
	v_readfirstlane_b32 s11, v108
	v_lshl_add_u64 v[102:103], v[100:101], 0, s[12:13]
	s_mov_b64 s[12:13], 0x80
	s_lshl_b32 s11, s11, 10
	v_add_u32_e32 v110, 0xc000, v55
	v_add_u32_e32 v111, 0xc000, v56
	v_add_u32_e32 v112, 0xc000, v57
	v_add_u32_e32 v113, 0xc000, v58
	s_mov_b32 m0, s11
	s_nop 0
	global_load_lds_dwordx4 v[100:101], off
	s_add_u32 m0, s11, 0x2000
	v_lshl_add_u64 v[100:101], v[100:101], 0, s[12:13]
	global_load_lds_dwordx4 v[102:103], off
	s_add_u32 m0, s11, 0x4000
	v_lshl_add_u64 v[102:103], v[102:103], 0, s[12:13]
	global_load_lds_dwordx4 v[104:105], off
	v_lshl_add_u64 v[104:105], v[104:105], 0, s[12:13]
	s_add_u32 m0, s11, 0x6000
	s_nop 0
	global_load_lds_dwordx4 v[100:101], off
	s_add_u32 m0, s11, 0x8000
	v_lshl_add_u64 v[100:101], v[100:101], 0, s[12:13]
	global_load_lds_dwordx4 v[102:103], off
	s_add_u32 m0, s11, 0xa000
	v_lshl_add_u64 v[102:103], v[102:103], 0, s[12:13]
	global_load_lds_dwordx4 v[104:105], off
	v_lshl_add_u64 v[104:105], v[104:105], 0, s[12:13]
	s_add_u32 m0, s11, 0xc000
	s_nop 0
	global_load_lds_dwordx4 v[100:101], off
	s_add_u32 m0, s11, 0xe000
	v_lshl_add_u64 v[100:101], v[100:101], 0, s[12:13]
	global_load_lds_dwordx4 v[102:103], off
	s_add_u32 m0, s11, 0x10000
	v_lshl_add_u64 v[102:103], v[102:103], 0, s[12:13]
	global_load_lds_dwordx4 v[104:105], off
	v_lshl_add_u64 v[104:105], v[104:105], 0, s[12:13]
	s_mov_b32 s6, 0
.Lpcs_g_loop:
	s_waitcnt vmcnt(6)
	s_barrier
	s_add_u32 m0, s11, 0x12000
	s_nop 0
	global_load_lds_dwordx4 v[100:101], off
	s_add_u32 m0, s11, 0x14000
	v_lshl_add_u64 v[100:101], v[100:101], 0, s[12:13]
	global_load_lds_dwordx4 v[102:103], off
	s_add_u32 m0, s11, 0x16000
	v_lshl_add_u64 v[102:103], v[102:103], 0, s[12:13]
	global_load_lds_dwordx4 v[104:105], off
	v_lshl_add_u64 v[104:105], v[104:105], 0, s[12:13]
	ds_read_b128 v[60:63], v55 offset:16384
	ds_read_b128 v[64:67], v57
	ds_read_b128 v[68:71], v57 offset:2048
	ds_read_b128 v[72:75], v57 offset:4096
	ds_read_b128 v[76:79], v57 offset:6144
	ds_read_b128 v[80:83], v56 offset:16384
	ds_read_b128 v[84:87], v58
	ds_read_b128 v[88:91], v58 offset:2048
	ds_read_b128 v[92:95], v58 offset:4096
	ds_read_b128 v[96:99], v58 offset:6144
	s_waitcnt lgkmcnt(8)
	v_mfma_f32_16x16x32_bf16 v[26:29], v[60:63], v[64:67], v[26:29]
	s_waitcnt lgkmcnt(7)
	v_mfma_f32_16x16x32_bf16 v[30:33], v[60:63], v[68:71], v[30:33]
	s_waitcnt lgkmcnt(6)
	v_mfma_f32_16x16x32_bf16 v[38:41], v[60:63], v[72:75], v[38:41]
	s_waitcnt lgkmcnt(5)
	v_mfma_f32_16x16x32_bf16 v[34:37], v[60:63], v[76:79], v[34:37]
	s_waitcnt lgkmcnt(3)
	v_mfma_f32_16x16x32_bf16 v[26:29], v[80:83], v[84:87], v[26:29]
	s_waitcnt lgkmcnt(2)
	v_mfma_f32_16x16x32_bf16 v[30:33], v[80:83], v[88:91], v[30:33]
	s_waitcnt lgkmcnt(1)
	v_mfma_f32_16x16x32_bf16 v[38:41], v[80:83], v[92:95], v[38:41]
	s_waitcnt lgkmcnt(0)
	v_mfma_f32_16x16x32_bf16 v[34:37], v[80:83], v[96:99], v[34:37]
	s_waitcnt vmcnt(6)
	s_barrier
	s_mov_b32 m0, s11
	s_nop 0
	global_load_lds_dwordx4 v[100:101], off
	s_add_u32 m0, s11, 0x2000
	v_lshl_add_u64 v[100:101], v[100:101], 0, s[12:13]
	global_load_lds_dwordx4 v[102:103], off
	s_add_u32 m0, s11, 0x4000
	v_lshl_add_u64 v[102:103], v[102:103], 0, s[12:13]
	global_load_lds_dwordx4 v[104:105], off
	v_lshl_add_u64 v[104:105], v[104:105], 0, s[12:13]
	ds_read_b128 v[60:63], v55 offset:40960
	ds_read_b128 v[64:67], v57 offset:24576
	ds_read_b128 v[68:71], v57 offset:26624
	ds_read_b128 v[72:75], v57 offset:28672
	ds_read_b128 v[76:79], v57 offset:30720
	ds_read_b128 v[80:83], v56 offset:40960
	ds_read_b128 v[84:87], v58 offset:24576
	ds_read_b128 v[88:91], v58 offset:26624
	ds_read_b128 v[92:95], v58 offset:28672
	ds_read_b128 v[96:99], v58 offset:30720
	s_waitcnt lgkmcnt(8)
	v_mfma_f32_16x16x32_bf16 v[26:29], v[60:63], v[64:67], v[26:29]
	s_waitcnt lgkmcnt(7)
	v_mfma_f32_16x16x32_bf16 v[30:33], v[60:63], v[68:71], v[30:33]
	s_waitcnt lgkmcnt(6)
	v_mfma_f32_16x16x32_bf16 v[38:41], v[60:63], v[72:75], v[38:41]
	s_waitcnt lgkmcnt(5)
	v_mfma_f32_16x16x32_bf16 v[34:37], v[60:63], v[76:79], v[34:37]
	s_waitcnt lgkmcnt(3)
	v_mfma_f32_16x16x32_bf16 v[26:29], v[80:83], v[84:87], v[26:29]
	s_waitcnt lgkmcnt(2)
	v_mfma_f32_16x16x32_bf16 v[30:33], v[80:83], v[88:91], v[30:33]
	s_waitcnt lgkmcnt(1)
	v_mfma_f32_16x16x32_bf16 v[38:41], v[80:83], v[92:95], v[38:41]
	s_waitcnt lgkmcnt(0)
	v_mfma_f32_16x16x32_bf16 v[34:37], v[80:83], v[96:99], v[34:37]
	s_waitcnt vmcnt(6)
	s_barrier
	s_add_u32 m0, s11, 0x6000
	s_nop 0
	global_load_lds_dwordx4 v[100:101], off
	s_add_u32 m0, s11, 0x8000
	v_lshl_add_u64 v[100:101], v[100:101], 0, s[12:13]
	global_load_lds_dwordx4 v[102:103], off
	s_add_u32 m0, s11, 0xa000
	v_lshl_add_u64 v[102:103], v[102:103], 0, s[12:13]
	global_load_lds_dwordx4 v[104:105], off
	v_lshl_add_u64 v[104:105], v[104:105], 0, s[12:13]
	ds_read_b128 v[60:63], v110 offset:16384
	ds_read_b128 v[64:67], v112
	ds_read_b128 v[68:71], v112 offset:2048
	ds_read_b128 v[72:75], v112 offset:4096
	ds_read_b128 v[76:79], v112 offset:6144
	ds_read_b128 v[80:83], v111 offset:16384
	ds_read_b128 v[84:87], v113
	ds_read_b128 v[88:91], v113 offset:2048
	ds_read_b128 v[92:95], v113 offset:4096
	ds_read_b128 v[96:99], v113 offset:6144
	s_waitcnt lgkmcnt(8)
	v_mfma_f32_16x16x32_bf16 v[26:29], v[60:63], v[64:67], v[26:29]
	s_waitcnt lgkmcnt(7)
	v_mfma_f32_16x16x32_bf16 v[30:33], v[60:63], v[68:71], v[30:33]
	s_waitcnt lgkmcnt(6)
	v_mfma_f32_16x16x32_bf16 v[38:41], v[60:63], v[72:75], v[38:41]
	s_waitcnt lgkmcnt(5)
	v_mfma_f32_16x16x32_bf16 v[34:37], v[60:63], v[76:79], v[34:37]
	s_waitcnt lgkmcnt(3)
	v_mfma_f32_16x16x32_bf16 v[26:29], v[80:83], v[84:87], v[26:29]
	s_waitcnt lgkmcnt(2)
	v_mfma_f32_16x16x32_bf16 v[30:33], v[80:83], v[88:91], v[30:33]
	s_waitcnt lgkmcnt(1)
	v_mfma_f32_16x16x32_bf16 v[38:41], v[80:83], v[92:95], v[38:41]
	s_waitcnt lgkmcnt(0)
	v_mfma_f32_16x16x32_bf16 v[34:37], v[80:83], v[96:99], v[34:37]
	s_waitcnt vmcnt(6)
	s_barrier
	s_add_u32 m0, s11, 0xc000
	s_nop 0
	global_load_lds_dwordx4 v[100:101], off
	s_add_u32 m0, s11, 0xe000
	v_lshl_add_u64 v[100:101], v[100:101], 0, s[12:13]
	global_load_lds_dwordx4 v[102:103], off
	s_add_u32 m0, s11, 0x10000
	v_lshl_add_u64 v[102:103], v[102:103], 0, s[12:13]
	global_load_lds_dwordx4 v[104:105], off
	v_lshl_add_u64 v[104:105], v[104:105], 0, s[12:13]
	ds_read_b128 v[60:63], v110 offset:40960
	ds_read_b128 v[64:67], v112 offset:24576
	ds_read_b128 v[68:71], v112 offset:26624
	ds_read_b128 v[72:75], v112 offset:28672
	ds_read_b128 v[76:79], v112 offset:30720
	ds_read_b128 v[80:83], v111 offset:40960
	ds_read_b128 v[84:87], v113 offset:24576
	ds_read_b128 v[88:91], v113 offset:26624
	ds_read_b128 v[92:95], v113 offset:28672
	ds_read_b128 v[96:99], v113 offset:30720
	s_waitcnt lgkmcnt(8)
	v_mfma_f32_16x16x32_bf16 v[26:29], v[60:63], v[64:67], v[26:29]
	s_waitcnt lgkmcnt(7)
	v_mfma_f32_16x16x32_bf16 v[30:33], v[60:63], v[68:71], v[30:33]
	s_waitcnt lgkmcnt(6)
	v_mfma_f32_16x16x32_bf16 v[38:41], v[60:63], v[72:75], v[38:41]
	s_waitcnt lgkmcnt(5)
	v_mfma_f32_16x16x32_bf16 v[34:37], v[60:63], v[76:79], v[34:37]
	s_waitcnt lgkmcnt(3)
	v_mfma_f32_16x16x32_bf16 v[26:29], v[80:83], v[84:87], v[26:29]
	s_waitcnt lgkmcnt(2)
	v_mfma_f32_16x16x32_bf16 v[30:33], v[80:83], v[88:91], v[30:33]
	s_waitcnt lgkmcnt(1)
	v_mfma_f32_16x16x32_bf16 v[38:41], v[80:83], v[92:95], v[38:41]
	s_waitcnt lgkmcnt(0)
	v_mfma_f32_16x16x32_bf16 v[34:37], v[80:83], v[96:99], v[34:37]
	s_add_i32 s6, s6, 1
	s_cmp_lt_u32 s6, 7
	s_cbranch_scc1 .Lpcs_g_loop
	s_waitcnt vmcnt(6)
	s_barrier
	s_add_u32 m0, s11, 0x12000
	s_nop 0
	global_load_lds_dwordx4 v[100:101], off
	s_add_u32 m0, s11, 0x14000
	v_lshl_add_u64 v[100:101], v[100:101], 0, s[12:13]
	global_load_lds_dwordx4 v[102:103], off
	s_add_u32 m0, s11, 0x16000
	v_lshl_add_u64 v[102:103], v[102:103], 0, s[12:13]
	global_load_lds_dwordx4 v[104:105], off
	v_lshl_add_u64 v[104:105], v[104:105], 0, s[12:13]
	ds_read_b128 v[60:63], v55 offset:16384
	ds_read_b128 v[64:67], v57
	ds_read_b128 v[68:71], v57 offset:2048
	ds_read_b128 v[72:75], v57 offset:4096
	ds_read_b128 v[76:79], v57 offset:6144
	ds_read_b128 v[80:83], v56 offset:16384
	ds_read_b128 v[84:87], v58
	ds_read_b128 v[88:91], v58 offset:2048
	ds_read_b128 v[92:95], v58 offset:4096
	ds_read_b128 v[96:99], v58 offset:6144
	s_waitcnt lgkmcnt(8)
	v_mfma_f32_16x16x32_bf16 v[26:29], v[60:63], v[64:67], v[26:29]
	s_waitcnt lgkmcnt(7)
	v_mfma_f32_16x16x32_bf16 v[30:33], v[60:63], v[68:71], v[30:33]
	s_waitcnt lgkmcnt(6)
	v_mfma_f32_16x16x32_bf16 v[38:41], v[60:63], v[72:75], v[38:41]
	s_waitcnt lgkmcnt(5)
	v_mfma_f32_16x16x32_bf16 v[34:37], v[60:63], v[76:79], v[34:37]
	s_waitcnt lgkmcnt(3)
	v_mfma_f32_16x16x32_bf16 v[26:29], v[80:83], v[84:87], v[26:29]
	s_waitcnt lgkmcnt(2)
	v_mfma_f32_16x16x32_bf16 v[30:33], v[80:83], v[88:91], v[30:33]
	s_waitcnt lgkmcnt(1)
	v_mfma_f32_16x16x32_bf16 v[38:41], v[80:83], v[92:95], v[38:41]
	s_waitcnt lgkmcnt(0)
	v_mfma_f32_16x16x32_bf16 v[34:37], v[80:83], v[96:99], v[34:37]
	s_waitcnt vmcnt(6)
	s_barrier
	ds_read_b128 v[60:63], v55 offset:40960
	ds_read_b128 v[64:67], v57 offset:24576
	ds_read_b128 v[68:71], v57 offset:26624
	ds_read_b128 v[72:75], v57 offset:28672
	ds_read_b128 v[76:79], v57 offset:30720
	ds_read_b128 v[80:83], v56 offset:40960
	ds_read_b128 v[84:87], v58 offset:24576
	ds_read_b128 v[88:91], v58 offset:26624
	ds_read_b128 v[92:95], v58 offset:28672
	ds_read_b128 v[96:99], v58 offset:30720
	s_waitcnt lgkmcnt(8)
	v_mfma_f32_16x16x32_bf16 v[26:29], v[60:63], v[64:67], v[26:29]
	s_waitcnt lgkmcnt(7)
	v_mfma_f32_16x16x32_bf16 v[30:33], v[60:63], v[68:71], v[30:33]
	s_waitcnt lgkmcnt(6)
	v_mfma_f32_16x16x32_bf16 v[38:41], v[60:63], v[72:75], v[38:41]
	s_waitcnt lgkmcnt(5)
	v_mfma_f32_16x16x32_bf16 v[34:37], v[60:63], v[76:79], v[34:37]
	s_waitcnt lgkmcnt(3)
	v_mfma_f32_16x16x32_bf16 v[26:29], v[80:83], v[84:87], v[26:29]
	s_waitcnt lgkmcnt(2)
	v_mfma_f32_16x16x32_bf16 v[30:33], v[80:83], v[88:91], v[30:33]
	s_waitcnt lgkmcnt(1)
	v_mfma_f32_16x16x32_bf16 v[38:41], v[80:83], v[92:95], v[38:41]
	s_waitcnt lgkmcnt(0)
	v_mfma_f32_16x16x32_bf16 v[34:37], v[80:83], v[96:99], v[34:37]
	s_waitcnt vmcnt(3)
	s_barrier
	ds_read_b128 v[60:63], v110 offset:16384
	ds_read_b128 v[64:67], v112
	ds_read_b128 v[68:71], v112 offset:2048
	ds_read_b128 v[72:75], v112 offset:4096
	ds_read_b128 v[76:79], v112 offset:6144
	ds_read_b128 v[80:83], v111 offset:16384
	ds_read_b128 v[84:87], v113
	ds_read_b128 v[88:91], v113 offset:2048
	ds_read_b128 v[92:95], v113 offset:4096
	ds_read_b128 v[96:99], v113 offset:6144
	s_waitcnt lgkmcnt(8)
	v_mfma_f32_16x16x32_bf16 v[26:29], v[60:63], v[64:67], v[26:29]
	s_waitcnt lgkmcnt(7)
	v_mfma_f32_16x16x32_bf16 v[30:33], v[60:63], v[68:71], v[30:33]
	s_waitcnt lgkmcnt(6)
	v_mfma_f32_16x16x32_bf16 v[38:41], v[60:63], v[72:75], v[38:41]
	s_waitcnt lgkmcnt(5)
	v_mfma_f32_16x16x32_bf16 v[34:37], v[60:63], v[76:79], v[34:37]
	s_waitcnt lgkmcnt(3)
	v_mfma_f32_16x16x32_bf16 v[26:29], v[80:83], v[84:87], v[26:29]
	s_waitcnt lgkmcnt(2)
	v_mfma_f32_16x16x32_bf16 v[30:33], v[80:83], v[88:91], v[30:33]
	s_waitcnt lgkmcnt(1)
	v_mfma_f32_16x16x32_bf16 v[38:41], v[80:83], v[92:95], v[38:41]
	s_waitcnt lgkmcnt(0)
	v_mfma_f32_16x16x32_bf16 v[34:37], v[80:83], v[96:99], v[34:37]
	s_waitcnt vmcnt(0)
	s_barrier
	ds_read_b128 v[60:63], v110 offset:40960
	ds_read_b128 v[64:67], v112 offset:24576
	ds_read_b128 v[68:71], v112 offset:26624
	ds_read_b128 v[72:75], v112 offset:28672
	ds_read_b128 v[76:79], v112 offset:30720
	ds_read_b128 v[80:83], v111 offset:40960
	ds_read_b128 v[84:87], v113 offset:24576
	ds_read_b128 v[88:91], v113 offset:26624
	ds_read_b128 v[92:95], v113 offset:28672
	ds_read_b128 v[96:99], v113 offset:30720
	s_waitcnt lgkmcnt(8)
	v_mfma_f32_16x16x32_bf16 v[26:29], v[60:63], v[64:67], v[26:29]
	s_waitcnt lgkmcnt(7)
	v_mfma_f32_16x16x32_bf16 v[30:33], v[60:63], v[68:71], v[30:33]
	s_waitcnt lgkmcnt(6)
	v_mfma_f32_16x16x32_bf16 v[38:41], v[60:63], v[72:75], v[38:41]
	s_waitcnt lgkmcnt(5)
	v_mfma_f32_16x16x32_bf16 v[34:37], v[60:63], v[76:79], v[34:37]
	s_waitcnt lgkmcnt(3)
	v_mfma_f32_16x16x32_bf16 v[26:29], v[80:83], v[84:87], v[26:29]
	s_waitcnt lgkmcnt(2)
	v_mfma_f32_16x16x32_bf16 v[30:33], v[80:83], v[88:91], v[30:33]
	s_waitcnt lgkmcnt(1)
	v_mfma_f32_16x16x32_bf16 v[38:41], v[80:83], v[92:95], v[38:41]
	s_waitcnt lgkmcnt(0)
	v_mfma_f32_16x16x32_bf16 v[34:37], v[80:83], v[96:99], v[34:37]
	s_branch .LBB0_74
.LBB0_81:
	s_or_b64 exec, exec, s[0:1]
	v_readlane_b32 s50, v253, 47
	v_readlane_b32 s51, v253, 48
	v_and_b32_e32 v130, 63, v206
	v_lshrrev_b32_e32 v131, 6, v206
	v_and_b32_e32 v132, 15, v206
	v_bfe_u32 v133, v206, 4, 2
	v_and_b32_e32 v134, 3, v131
	v_lshrrev_b32_e32 v135, 2, v131
	v_readfirstlane_b32 s0, v131
	s_mul_i32 s1, s8, 0x2c00
	s_lshl_b32 s7, s6, 1
	s_add_u32 s12, s50, s1
	s_addc_u32 s13, s51, 0
	s_add_u32 s12, s12, s7
	s_addc_u32 s13, s13, 0
	v_lshrrev_b32_e32 v136, 1, v133
	v_lshl_add_u32 v136, v134, 2, v136
	v_and_b32_e32 v137, 1, v133
	v_lshlrev_b32_e32 v137, 3, v137
	v_lshl_add_u32 v138, v135, 6, v132
	v_lshlrev_b32_e32 v139, 9, v138
	v_add_u32_e32 v139, v139, v137
	v_mov_b32_e32 v140, v136
	v_xor_b32_e32 v140, v140, v132
	v_lshl_add_u32 v144, v140, 4, v139
	v_add_u32_e32 v146, 0x10000, v144
	v_add_u32_e32 v140, 2, v136
	v_xor_b32_e32 v140, v140, v132
	v_lshl_add_u32 v145, v140, 4, v139
	v_add_u32_e32 v147, 0x10000, v145
	v_cvt_pk_bf16_f32 v148, v118, v119
	v_cvt_pk_bf16_f32 v149, v120, v121
	ds_write_b64 v144, v[148:149]
	v_cvt_pk_bf16_f32 v150, v110, v111
	v_cvt_pk_bf16_f32 v151, v112, v113
	ds_write_b64 v145, v[150:151]
	v_cvt_pk_bf16_f32 v152, v126, v127
	v_cvt_pk_bf16_f32 v153, v128, v129
	ds_write_b64 v144, v[152:153] offset:256
	v_cvt_pk_bf16_f32 v154, v122, v123
	v_cvt_pk_bf16_f32 v155, v124, v125
	ds_write_b64 v145, v[154:155] offset:256
	v_cvt_pk_bf16_f32 v156, v102, v103
	v_cvt_pk_bf16_f32 v157, v104, v105
	ds_write_b64 v144, v[156:157] offset:8192
	v_cvt_pk_bf16_f32 v158, v94, v95
	v_cvt_pk_bf16_f32 v159, v96, v97
	ds_write_b64 v145, v[158:159] offset:8192
	v_cvt_pk_bf16_f32 v160, v114, v115
	v_cvt_pk_bf16_f32 v161, v116, v117
	ds_write_b64 v144, v[160:161] offset:8448
	v_cvt_pk_bf16_f32 v162, v106, v107
	v_cvt_pk_bf16_f32 v163, v108, v109
	ds_write_b64 v145, v[162:163] offset:8448
	v_cvt_pk_bf16_f32 v148, v74, v75
	v_cvt_pk_bf16_f32 v149, v76, v77
	ds_write_b64 v144, v[148:149] offset:16384
	v_cvt_pk_bf16_f32 v150, v62, v63
	v_cvt_pk_bf16_f32 v151, v64, v65
	ds_write_b64 v145, v[150:151] offset:16384
	v_cvt_pk_bf16_f32 v152, v98, v99
	v_cvt_pk_bf16_f32 v153, v100, v101
	ds_write_b64 v144, v[152:153] offset:16640
	v_cvt_pk_bf16_f32 v154, v90, v91
	v_cvt_pk_bf16_f32 v155, v92, v93
	ds_write_b64 v145, v[154:155] offset:16640
	v_cvt_pk_bf16_f32 v156, v42, v43
	v_cvt_pk_bf16_f32 v157, v44, v45
	ds_write_b64 v144, v[156:157] offset:24576
	v_cvt_pk_bf16_f32 v158, v34, v35
	v_cvt_pk_bf16_f32 v159, v36, v37
	ds_write_b64 v145, v[158:159] offset:24576
	v_cvt_pk_bf16_f32 v160, v66, v67
	v_cvt_pk_bf16_f32 v161, v68, v69
	ds_write_b64 v144, v[160:161] offset:24832
	v_cvt_pk_bf16_f32 v162, v58, v59
	v_cvt_pk_bf16_f32 v163, v60, v61
	ds_write_b64 v145, v[162:163] offset:24832
	v_cvt_pk_bf16_f32 v148, v78, v79
	v_cvt_pk_bf16_f32 v149, v80, v81
	ds_write_b64 v146, v[148:149]
	v_cvt_pk_bf16_f32 v150, v70, v71
	v_cvt_pk_bf16_f32 v151, v72, v73
	ds_write_b64 v147, v[150:151]
	v_cvt_pk_bf16_f32 v152, v86, v87
	v_cvt_pk_bf16_f32 v153, v88, v89
	ds_write_b64 v146, v[152:153] offset:256
	v_cvt_pk_bf16_f32 v154, v82, v83
	v_cvt_pk_bf16_f32 v155, v84, v85
	ds_write_b64 v147, v[154:155] offset:256
	v_cvt_pk_bf16_f32 v156, v46, v47
	v_cvt_pk_bf16_f32 v157, v48, v49
	ds_write_b64 v146, v[156:157] offset:8192
	v_cvt_pk_bf16_f32 v158, v38, v39
	v_cvt_pk_bf16_f32 v159, v40, v41
	ds_write_b64 v147, v[158:159] offset:8192
	v_cvt_pk_bf16_f32 v160, v54, v55
	v_cvt_pk_bf16_f32 v161, v56, v57
	ds_write_b64 v146, v[160:161] offset:8448
	v_cvt_pk_bf16_f32 v162, v50, v51
	v_cvt_pk_bf16_f32 v163, v52, v53
	ds_write_b64 v147, v[162:163] offset:8448
	v_cvt_pk_bf16_f32 v148, v22, v23
	v_cvt_pk_bf16_f32 v149, v24, v25
	ds_write_b64 v146, v[148:149] offset:16384
	v_cvt_pk_bf16_f32 v150, v18, v19
	v_cvt_pk_bf16_f32 v151, v20, v21
	ds_write_b64 v147, v[150:151] offset:16384
	v_cvt_pk_bf16_f32 v152, v30, v31
	v_cvt_pk_bf16_f32 v153, v32, v33
	ds_write_b64 v146, v[152:153] offset:16640
	v_cvt_pk_bf16_f32 v154, v26, v27
	v_cvt_pk_bf16_f32 v155, v28, v29
	ds_write_b64 v147, v[154:155] offset:16640
	v_cvt_pk_bf16_f32 v156, v6, v7
	v_cvt_pk_bf16_f32 v157, v8, v9
	ds_write_b64 v146, v[156:157] offset:24576
	v_cvt_pk_bf16_f32 v158, v2, v3
	v_cvt_pk_bf16_f32 v159, v4, v5
	ds_write_b64 v147, v[158:159] offset:24576
	v_cvt_pk_bf16_f32 v160, v14, v15
	v_cvt_pk_bf16_f32 v161, v16, v17
	ds_write_b64 v146, v[160:161] offset:24832
	v_cvt_pk_bf16_f32 v162, v10, v11
	v_cvt_pk_bf16_f32 v163, v12, v13
	ds_write_b64 v147, v[162:163] offset:24832
	v_lshlrev_b32_e32 v140, 4, v130
	v_lshl_add_u32 v140, v131, 10, v140
	v_lshrrev_b32_e32 v136, 5, v130
	v_lshl_add_u32 v137, v131, 1, v136
	v_and_b32_e32 v138, 31, v130
	v_xor_b32_e32 v138, v138, v137
	v_mul_u32_u24_e32 v139, 0x2c00, v137
	v_lshl_add_u32 v139, v138, 4, v139
	s_waitcnt lgkmcnt(0)
	s_barrier
	v_add_u32_e32 v141, 0x10000, v140
	ds_read_b128 v[2:5], v140
	ds_read_b128 v[6:9], v140 offset:8192
	ds_read_b128 v[10:13], v140 offset:16384
	ds_read_b128 v[14:17], v140 offset:24576
	ds_read_b128 v[18:21], v140 offset:32768
	ds_read_b128 v[22:25], v140 offset:40960
	ds_read_b128 v[26:29], v140 offset:49152
	ds_read_b128 v[30:33], v140 offset:57344
	s_waitcnt lgkmcnt(7)
	global_store_dwordx4 v139, v[2:5], s[12:13]
	ds_read_b128 v[34:37], v141
	s_add_u32 s12, s12, 0x2c000
	s_addc_u32 s13, s13, 0
	s_waitcnt lgkmcnt(7)
	global_store_dwordx4 v139, v[6:9], s[12:13]
	ds_read_b128 v[38:41], v141 offset:8192
	s_add_u32 s12, s12, 0x2c000
	s_addc_u32 s13, s13, 0
	s_waitcnt lgkmcnt(7)
	global_store_dwordx4 v139, v[10:13], s[12:13]
	ds_read_b128 v[42:45], v141 offset:16384
	s_add_u32 s12, s12, 0x2c000
	s_addc_u32 s13, s13, 0
	s_waitcnt lgkmcnt(7)
	global_store_dwordx4 v139, v[14:17], s[12:13]
	ds_read_b128 v[46:49], v141 offset:24576
	s_add_u32 s12, s12, 0x2c000
	s_addc_u32 s13, s13, 0
	s_waitcnt lgkmcnt(7)
	global_store_dwordx4 v139, v[18:21], s[12:13]
	ds_read_b128 v[50:53], v141 offset:32768
	s_add_u32 s12, s12, 0x2c000
	s_addc_u32 s13, s13, 0
	s_waitcnt lgkmcnt(7)
	global_store_dwordx4 v139, v[22:25], s[12:13]
	ds_read_b128 v[54:57], v141 offset:40960
	s_add_u32 s12, s12, 0x2c000
	s_addc_u32 s13, s13, 0
	s_waitcnt lgkmcnt(7)
	global_store_dwordx4 v139, v[26:29], s[12:13]
	ds_read_b128 v[58:61], v141 offset:49152
	s_add_u32 s12, s12, 0x2c000
	s_addc_u32 s13, s13, 0
	s_waitcnt lgkmcnt(7)
	global_store_dwordx4 v139, v[30:33], s[12:13]
	ds_read_b128 v[62:65], v141 offset:57344
	s_add_u32 s12, s12, 0x2c000
	s_addc_u32 s13, s13, 0
	s_waitcnt lgkmcnt(7)
	global_store_dwordx4 v139, v[34:37], s[12:13]
	s_add_u32 s12, s12, 0x2c000
	s_addc_u32 s13, s13, 0
	s_waitcnt lgkmcnt(6)
	global_store_dwordx4 v139, v[38:41], s[12:13]
	s_add_u32 s12, s12, 0x2c000
	s_addc_u32 s13, s13, 0
	s_waitcnt lgkmcnt(5)
	global_store_dwordx4 v139, v[42:45], s[12:13]
	s_add_u32 s12, s12, 0x2c000
	s_addc_u32 s13, s13, 0
	s_waitcnt lgkmcnt(4)
	global_store_dwordx4 v139, v[46:49], s[12:13]
	s_add_u32 s12, s12, 0x2c000
	s_addc_u32 s13, s13, 0
	s_waitcnt lgkmcnt(3)
	global_store_dwordx4 v139, v[50:53], s[12:13]
	s_add_u32 s12, s12, 0x2c000
	s_addc_u32 s13, s13, 0
	s_waitcnt lgkmcnt(2)
	global_store_dwordx4 v139, v[54:57], s[12:13]
	s_add_u32 s12, s12, 0x2c000
	s_addc_u32 s13, s13, 0
	s_waitcnt lgkmcnt(1)
	global_store_dwordx4 v139, v[58:61], s[12:13]
	s_add_u32 s12, s12, 0x2c000
	s_addc_u32 s13, s13, 0
	s_waitcnt lgkmcnt(0)
	global_store_dwordx4 v139, v[62:65], s[12:13]
	v_readlane_b32 s36, v253, 33
	v_readlane_b32 s37, v253, 34
	v_readlane_b32 s38, v253, 35
	v_readlane_b32 s39, v253, 36
	v_readlane_b32 s40, v253, 37
	v_readlane_b32 s41, v253, 38
	v_readlane_b32 s42, v253, 39
	v_readlane_b32 s43, v253, 40
	v_readlane_b32 s44, v253, 41
	v_readlane_b32 s45, v253, 42
	v_readlane_b32 s46, v253, 43
	v_readlane_b32 s47, v253, 44
	v_readlane_b32 s48, v253, 45
	v_readlane_b32 s49, v253, 46
	v_readlane_b32 s50, v253, 47
	v_readlane_b32 s51, v253, 48
	s_add_i32 s56, s56, s96
	s_cmpk_gt_i32 s56, 0x3ff
	s_cbranch_scc1 .LBB0_88

.LBB0_674:
	s_or_b64 exec, exec, s[0:1]
	v_and_b32_e32 v130, 63, v206
	v_lshrrev_b32_e32 v131, 6, v206
	v_and_b32_e32 v132, 15, v206
	v_bfe_u32 v133, v206, 4, 2
	v_and_b32_e32 v134, 3, v131
	v_lshrrev_b32_e32 v135, 2, v131
	v_readfirstlane_b32 s0, v131
	s_mul_i32 s1, s6, 0x1c00
	s_lshl_b32 s7, s4, 1
	s_add_u32 s12, s90, s1
	s_addc_u32 s13, s91, 0
	s_add_u32 s12, s12, s7
	s_addc_u32 s13, s13, 0
	v_lshrrev_b32_e32 v136, 1, v133
	v_lshl_add_u32 v136, v134, 2, v136
	v_and_b32_e32 v137, 1, v133
	v_lshlrev_b32_e32 v137, 3, v137
	v_lshl_add_u32 v138, v135, 6, v132
	v_lshlrev_b32_e32 v139, 9, v138
	v_add_u32_e32 v139, v139, v137
	v_mov_b32_e32 v140, v136
	v_xor_b32_e32 v140, v140, v132
	v_lshl_add_u32 v144, v140, 4, v139
	v_add_u32_e32 v146, 0x10000, v144
	v_add_u32_e32 v140, 2, v136
	v_xor_b32_e32 v140, v140, v132
	v_lshl_add_u32 v145, v140, 4, v139
	v_add_u32_e32 v147, 0x10000, v145
	v_cvt_pk_bf16_f32 v148, v118, v119
	v_cvt_pk_bf16_f32 v149, v120, v121
	ds_write_b64 v144, v[148:149]
	v_cvt_pk_bf16_f32 v150, v110, v111
	v_cvt_pk_bf16_f32 v151, v112, v113
	ds_write_b64 v145, v[150:151]
	v_cvt_pk_bf16_f32 v152, v126, v127
	v_cvt_pk_bf16_f32 v153, v128, v129
	ds_write_b64 v144, v[152:153] offset:256
	v_cvt_pk_bf16_f32 v154, v122, v123
	v_cvt_pk_bf16_f32 v155, v124, v125
	ds_write_b64 v145, v[154:155] offset:256
	v_cvt_pk_bf16_f32 v156, v102, v103
	v_cvt_pk_bf16_f32 v157, v104, v105
	ds_write_b64 v144, v[156:157] offset:8192
	v_cvt_pk_bf16_f32 v158, v94, v95
	v_cvt_pk_bf16_f32 v159, v96, v97
	ds_write_b64 v145, v[158:159] offset:8192
	v_cvt_pk_bf16_f32 v160, v114, v115
	v_cvt_pk_bf16_f32 v161, v116, v117
	ds_write_b64 v144, v[160:161] offset:8448
	v_cvt_pk_bf16_f32 v162, v106, v107
	v_cvt_pk_bf16_f32 v163, v108, v109
	ds_write_b64 v145, v[162:163] offset:8448
	v_cvt_pk_bf16_f32 v148, v74, v75
	v_cvt_pk_bf16_f32 v149, v76, v77
	ds_write_b64 v144, v[148:149] offset:16384
	v_cvt_pk_bf16_f32 v150, v62, v63
	v_cvt_pk_bf16_f32 v151, v64, v65
	ds_write_b64 v145, v[150:151] offset:16384
	v_cvt_pk_bf16_f32 v152, v98, v99
	v_cvt_pk_bf16_f32 v153, v100, v101
	ds_write_b64 v144, v[152:153] offset:16640
	v_cvt_pk_bf16_f32 v154, v90, v91
	v_cvt_pk_bf16_f32 v155, v92, v93
	ds_write_b64 v145, v[154:155] offset:16640
	v_cvt_pk_bf16_f32 v156, v42, v43
	v_cvt_pk_bf16_f32 v157, v44, v45
	ds_write_b64 v144, v[156:157] offset:24576
	v_cvt_pk_bf16_f32 v158, v34, v35
	v_cvt_pk_bf16_f32 v159, v36, v37
	ds_write_b64 v145, v[158:159] offset:24576
	v_cvt_pk_bf16_f32 v160, v66, v67
	v_cvt_pk_bf16_f32 v161, v68, v69
	ds_write_b64 v144, v[160:161] offset:24832
	v_cvt_pk_bf16_f32 v162, v58, v59
	v_cvt_pk_bf16_f32 v163, v60, v61
	ds_write_b64 v145, v[162:163] offset:24832
	v_cvt_pk_bf16_f32 v148, v78, v79
	v_cvt_pk_bf16_f32 v149, v80, v81
	ds_write_b64 v146, v[148:149]
	v_cvt_pk_bf16_f32 v150, v70, v71
	v_cvt_pk_bf16_f32 v151, v72, v73
	ds_write_b64 v147, v[150:151]
	v_cvt_pk_bf16_f32 v152, v86, v87
	v_cvt_pk_bf16_f32 v153, v88, v89
	ds_write_b64 v146, v[152:153] offset:256
	v_cvt_pk_bf16_f32 v154, v82, v83
	v_cvt_pk_bf16_f32 v155, v84, v85
	ds_write_b64 v147, v[154:155] offset:256
	v_cvt_pk_bf16_f32 v156, v46, v47
	v_cvt_pk_bf16_f32 v157, v48, v49
	ds_write_b64 v146, v[156:157] offset:8192
	v_cvt_pk_bf16_f32 v158, v38, v39
	v_cvt_pk_bf16_f32 v159, v40, v41
	ds_write_b64 v147, v[158:159] offset:8192
	v_cvt_pk_bf16_f32 v160, v54, v55
	v_cvt_pk_bf16_f32 v161, v56, v57
	ds_write_b64 v146, v[160:161] offset:8448
	v_cvt_pk_bf16_f32 v162, v50, v51
	v_cvt_pk_bf16_f32 v163, v52, v53
	ds_write_b64 v147, v[162:163] offset:8448
	v_cvt_pk_bf16_f32 v148, v22, v23
	v_cvt_pk_bf16_f32 v149, v24, v25
	ds_write_b64 v146, v[148:149] offset:16384
	v_cvt_pk_bf16_f32 v150, v18, v19
	v_cvt_pk_bf16_f32 v151, v20, v21
	ds_write_b64 v147, v[150:151] offset:16384
	v_cvt_pk_bf16_f32 v152, v30, v31
	v_cvt_pk_bf16_f32 v153, v32, v33
	ds_write_b64 v146, v[152:153] offset:16640
	v_cvt_pk_bf16_f32 v154, v26, v27
	v_cvt_pk_bf16_f32 v155, v28, v29
	ds_write_b64 v147, v[154:155] offset:16640
	v_cvt_pk_bf16_f32 v156, v6, v7
	v_cvt_pk_bf16_f32 v157, v8, v9
	ds_write_b64 v146, v[156:157] offset:24576
	v_cvt_pk_bf16_f32 v158, v2, v3
	v_cvt_pk_bf16_f32 v159, v4, v5
	ds_write_b64 v147, v[158:159] offset:24576
	v_cvt_pk_bf16_f32 v160, v14, v15
	v_cvt_pk_bf16_f32 v161, v16, v17
	ds_write_b64 v146, v[160:161] offset:24832
	v_cvt_pk_bf16_f32 v162, v10, v11
	v_cvt_pk_bf16_f32 v163, v12, v13
	ds_write_b64 v147, v[162:163] offset:24832
	v_lshlrev_b32_e32 v140, 4, v130
	v_lshl_add_u32 v140, v131, 10, v140
	v_lshrrev_b32_e32 v136, 5, v130
	v_lshl_add_u32 v137, v131, 1, v136
	v_and_b32_e32 v138, 31, v130
	v_xor_b32_e32 v138, v138, v137
	v_mul_u32_u24_e32 v139, 0x1c00, v137
	v_lshl_add_u32 v139, v138, 4, v139
	s_waitcnt lgkmcnt(0)
	s_barrier
	v_add_u32_e32 v141, 0x10000, v140
	ds_read_b128 v[2:5], v140
	ds_read_b128 v[6:9], v140 offset:8192
	ds_read_b128 v[10:13], v140 offset:16384
	ds_read_b128 v[14:17], v140 offset:24576
	ds_read_b128 v[18:21], v140 offset:32768
	ds_read_b128 v[22:25], v140 offset:40960
	ds_read_b128 v[26:29], v140 offset:49152
	ds_read_b128 v[30:33], v140 offset:57344
	s_waitcnt lgkmcnt(7)
	global_store_dwordx4 v139, v[2:5], s[12:13]
	ds_read_b128 v[34:37], v141
	s_add_u32 s12, s12, 0x1c000
	s_addc_u32 s13, s13, 0
	s_waitcnt lgkmcnt(7)
	global_store_dwordx4 v139, v[6:9], s[12:13]
	ds_read_b128 v[38:41], v141 offset:8192
	s_add_u32 s12, s12, 0x1c000
	s_addc_u32 s13, s13, 0
	s_waitcnt lgkmcnt(7)
	global_store_dwordx4 v139, v[10:13], s[12:13]
	ds_read_b128 v[42:45], v141 offset:16384
	s_add_u32 s12, s12, 0x1c000
	s_addc_u32 s13, s13, 0
	s_waitcnt lgkmcnt(7)
	global_store_dwordx4 v139, v[14:17], s[12:13]
	ds_read_b128 v[46:49], v141 offset:24576
	s_add_u32 s12, s12, 0x1c000
	s_addc_u32 s13, s13, 0
	s_waitcnt lgkmcnt(7)
	global_store_dwordx4 v139, v[18:21], s[12:13]
	ds_read_b128 v[50:53], v141 offset:32768
	s_add_u32 s12, s12, 0x1c000
	s_addc_u32 s13, s13, 0
	s_waitcnt lgkmcnt(7)
	global_store_dwordx4 v139, v[22:25], s[12:13]
	ds_read_b128 v[54:57], v141 offset:40960
	s_add_u32 s12, s12, 0x1c000
	s_addc_u32 s13, s13, 0
	s_waitcnt lgkmcnt(7)
	global_store_dwordx4 v139, v[26:29], s[12:13]
	ds_read_b128 v[58:61], v141 offset:49152
	s_add_u32 s12, s12, 0x1c000
	s_addc_u32 s13, s13, 0
	s_waitcnt lgkmcnt(7)
	global_store_dwordx4 v139, v[30:33], s[12:13]
	ds_read_b128 v[62:65], v141 offset:57344
	s_add_u32 s12, s12, 0x1c000
	s_addc_u32 s13, s13, 0
	s_waitcnt lgkmcnt(7)
	global_store_dwordx4 v139, v[34:37], s[12:13]
	s_add_u32 s12, s12, 0x1c000
	s_addc_u32 s13, s13, 0
	s_waitcnt lgkmcnt(6)
	global_store_dwordx4 v139, v[38:41], s[12:13]
	s_add_u32 s12, s12, 0x1c000
	s_addc_u32 s13, s13, 0
	s_waitcnt lgkmcnt(5)
	global_store_dwordx4 v139, v[42:45], s[12:13]
	s_add_u32 s12, s12, 0x1c000
	s_addc_u32 s13, s13, 0
	s_waitcnt lgkmcnt(4)
	global_store_dwordx4 v139, v[46:49], s[12:13]
	s_add_u32 s12, s12, 0x1c000
	s_addc_u32 s13, s13, 0
	s_waitcnt lgkmcnt(3)
	global_store_dwordx4 v139, v[50:53], s[12:13]
	s_add_u32 s12, s12, 0x1c000
	s_addc_u32 s13, s13, 0
	s_waitcnt lgkmcnt(2)
	global_store_dwordx4 v139, v[54:57], s[12:13]
	s_add_u32 s12, s12, 0x1c000
	s_addc_u32 s13, s13, 0
	s_waitcnt lgkmcnt(1)
	global_store_dwordx4 v139, v[58:61], s[12:13]
	s_add_u32 s12, s12, 0x1c000
	s_addc_u32 s13, s13, 0
	s_waitcnt lgkmcnt(0)
	global_store_dwordx4 v139, v[62:65], s[12:13]
	s_add_i32 s56, s56, s96
	s_cmpk_gt_i32 s56, 0x29f
	s_cbranch_scc1 .LBB0_1061
